# down GEMM walks its row panels in reverse (starts on the most recently written, cache-resident part of the MLP hidden tensor) on top of staggered GEMM starts
# speedup vs baseline: 1.0046x; 1.0046x over previous
;     __device__ bool next(int i, Unit& u) const {
;         const long L = (long)i * G + c; if (L >= nwg) return false;
;         int wgid = (int)L; { const int q = nwg / NXCD, r = nwg % NXCD, xcd = wgid % NXCD, off = wgid / NXCD; wgid = (xcd < r ? xcd * (q + 1) : r * (q + 1) + (xcd - r) * q) + off; }
;         const int nig = WGM * nN, gid = wgid / nig, fm = gid * WGM, gsz = (nM - fm) < WGM ? (nM - fm) : WGM;
;         u.pm = fm + ((wgid % nig) % gsz); u.pn = (wgid % nig) / gsz; return true;
;     }
; __global__ void __launch_bounds__(NWAVES * 64, 2) mega_fwd(Args args) {
;     ...
;             pg8::Gemm g{HB, Wdn_t, CR, DM, DFF, DFF, 0}; pg8::StaticOrder S; S.init(CR, DM, G, bx);
;             pg8::EpiRes<false> E{nullptr, XB + (size_t)row0 * DM, XB + (size_t)row0 * DM, ss3 + row0}; pg8::gemm_phase<pg8::EpiRes<false>, pg8::StaticOrder>(L, g, S, E);
.LBB0_1157:
	v_readlane_b32 s14, v248, 13
	s_add_i32 s14, s16, s14
	s_ashr_i32 s15, s14, 31
	s_lshr_b32 s15, s15, 26
	s_add_i32 s15, s14, s15
	s_ashr_i32 s16, s15, 6
	s_lshl_b32 s16, s16, 3
	s_sub_i32 s17, s34, s16
	s_min_i32 s17, s17, 8
	s_abs_i32 s19, s17
	v_cvt_f32_u32_e32 v0, s19
	s_sub_i32 s21, 0, s19
	s_andn2_b32 s15, s15, 63
	s_sub_i32 s14, s14, s15
	v_rcp_iflag_f32_e32 v0, v0
	s_abs_i32 s15, s14
	s_xor_b32 s20, s14, s17
	s_ashr_i32 s20, s20, 31
	v_mul_f32_e32 v0, 0x4f7ffffe, v0
	v_cvt_u32_f32_e32 v0, v0
	s_nop 0
	v_readfirstlane_b32 s22, v0
	s_mul_i32 s21, s21, s22
	s_mul_hi_u32 s21, s22, s21
	s_add_i32 s22, s22, s21
	s_mul_hi_u32 s21, s15, s22
	s_mul_i32 s22, s21, s19
	s_sub_i32 s15, s15, s22
	s_add_i32 s23, s21, 1
	s_sub_i32 s22, s15, s19
	s_cmp_ge_u32 s15, s19
	s_cselect_b32 s21, s23, s21
	s_cselect_b32 s15, s22, s15
	s_add_i32 s22, s21, 1
	s_cmp_ge_u32 s15, s19
	s_cselect_b32 s15, s22, s21
	s_xor_b32 s15, s15, s20
	s_sub_i32 s28, s15, s20
	s_mul_i32 s15, s28, s17
	s_sub_i32 s14, s14, s15
	s_add_i32 s30, s16, s14
	s_sub_i32 s30, s34, s30
	s_add_i32 s30, s30, -1

;     ...
;         const bool has_next = S.next(ui + 1, nxt);
;         const char* nA = has_next ? (const char*)g.A + (size_t)nxt.pm * tstepA : cA; const char* nB = has_next ? (const char*)g.Bt + (size_t)nxt.pn * tstepB : cB;
;     ...
; #pragma unroll
;         for (int a = 0; a < 2; ++a)
; #pragma unroll
;             for (int b = 0; b < 2; ++b)
; #pragma unroll
;                 for (int m = 0; m < 4; ++m)
; #pragma unroll
;                     for (int n = 0; n < 2; ++n) acc[a][b][m][n] = (f32x4){0.f, 0.f, 0.f, 0.f};
;         cur = nxt; cA = nA; cB = nB; ++ui;
.LBB0_1170:
	s_sub_i32 s22, s34, s22
	s_add_i32 s22, s22, -1
	s_ashr_i32 s23, s22, 31
	s_lshl_b64 s[24:25], s[22:23], 22
	s_add_u32 s24, s46, s24
	s_addc_u32 s25, s47, s25
	s_and_b64 s[26:27], s[4:5], exec
	s_cselect_b32 s23, s25, s37
	s_cselect_b32 s29, s24, s36
	s_ashr_i32 s21, s20, 31
	s_lshl_b64 s[26:27], s[20:21], 22
	s_add_u32 s26, s42, s26
	s_addc_u32 s27, s43, s27
	s_and_b64 s[40:41], s[4:5], exec
	s_cselect_b32 s21, s27, s39
	s_cselect_b32 s57, s26, s38
	s_add_u32 s36, s36, 0x200080
	s_addc_u32 s37, s37, 0
	s_add_u32 s58, s38, 0x100
	v_mov_b32_e32 v0, 0
	s_addc_u32 s59, s39, 0
	s_mov_b32 s60, -2
	v_mov_b32_e32 v1, v0
	v_mov_b32_e32 v2, v0
	v_mov_b32_e32 v3, v0
	v_mov_b32_e32 v4, v0
	v_mov_b32_e32 v5, v0
	v_mov_b32_e32 v6, v0
	v_mov_b32_e32 v7, v0
	v_mov_b32_e32 v16, v0
	v_mov_b32_e32 v17, v0
	v_mov_b32_e32 v18, v0
	v_mov_b32_e32 v19, v0
	v_mov_b32_e32 v20, v0
	v_mov_b32_e32 v21, v0
	v_mov_b32_e32 v22, v0
	v_mov_b32_e32 v23, v0
	v_mov_b32_e32 v32, v0
	v_mov_b32_e32 v33, v0
	v_mov_b32_e32 v34, v0
	v_mov_b32_e32 v35, v0
	v_mov_b32_e32 v36, v0
	v_mov_b32_e32 v37, v0
	v_mov_b32_e32 v38, v0
	v_mov_b32_e32 v39, v0
	v_mov_b32_e32 v48, v0
	v_mov_b32_e32 v49, v0
	v_mov_b32_e32 v50, v0
	v_mov_b32_e32 v51, v0
	v_mov_b32_e32 v52, v0
	v_mov_b32_e32 v53, v0
	v_mov_b32_e32 v54, v0
	v_mov_b32_e32 v55, v0
	v_mov_b32_e32 v8, v0
	v_mov_b32_e32 v9, v0
	v_mov_b32_e32 v10, v0
	v_mov_b32_e32 v11, v0
	v_mov_b32_e32 v12, v0
	v_mov_b32_e32 v13, v0
	v_mov_b32_e32 v14, v0
	v_mov_b32_e32 v15, v0
	v_mov_b32_e32 v24, v0
	v_mov_b32_e32 v25, v0
	v_mov_b32_e32 v26, v0
	v_mov_b32_e32 v27, v0
	v_mov_b32_e32 v28, v0
	v_mov_b32_e32 v29, v0
	v_mov_b32_e32 v30, v0
	v_mov_b32_e32 v31, v0
	v_mov_b32_e32 v40, v0
	v_mov_b32_e32 v41, v0
	v_mov_b32_e32 v42, v0
	v_mov_b32_e32 v43, v0
	v_mov_b32_e32 v44, v0
	v_mov_b32_e32 v45, v0
	v_mov_b32_e32 v46, v0
	v_mov_b32_e32 v47, v0
	v_mov_b32_e32 v56, v0
	v_mov_b32_e32 v57, v0
	v_mov_b32_e32 v58, v0
	v_mov_b32_e32 v59, v0
	v_mov_b32_e32 v60, v0
	v_mov_b32_e32 v61, v0
	v_mov_b32_e32 v62, v0
	v_mov_b32_e32 v63, v0
	v_mov_b32_e32 v64, v0
	v_mov_b32_e32 v65, v0
	v_mov_b32_e32 v66, v0
	v_mov_b32_e32 v67, v0
	v_mov_b32_e32 v68, v0
	v_mov_b32_e32 v69, v0
	v_mov_b32_e32 v70, v0
	v_mov_b32_e32 v71, v0
	v_mov_b32_e32 v80, v0
	v_mov_b32_e32 v81, v0
	v_mov_b32_e32 v82, v0
	v_mov_b32_e32 v83, v0
	v_mov_b32_e32 v84, v0
	v_mov_b32_e32 v85, v0
	v_mov_b32_e32 v86, v0
	v_mov_b32_e32 v87, v0
	v_mov_b32_e32 v96, v0
	v_mov_b32_e32 v97, v0
	v_mov_b32_e32 v98, v0
	v_mov_b32_e32 v99, v0
	v_mov_b32_e32 v100, v0
	v_mov_b32_e32 v101, v0
	v_mov_b32_e32 v102, v0
	v_mov_b32_e32 v103, v0
	v_mov_b32_e32 v112, v0
	v_mov_b32_e32 v113, v0
	v_mov_b32_e32 v114, v0
	v_mov_b32_e32 v115, v0
	v_mov_b32_e32 v116, v0
	v_mov_b32_e32 v117, v0
	v_mov_b32_e32 v118, v0
	v_mov_b32_e32 v119, v0
	v_mov_b32_e32 v72, v0
	v_mov_b32_e32 v73, v0
	v_mov_b32_e32 v74, v0
	v_mov_b32_e32 v75, v0
	v_mov_b32_e32 v76, v0
	v_mov_b32_e32 v77, v0
	v_mov_b32_e32 v78, v0
	v_mov_b32_e32 v79, v0
	v_mov_b32_e32 v88, v0
	v_mov_b32_e32 v89, v0
	v_mov_b32_e32 v90, v0
	v_mov_b32_e32 v91, v0
	v_mov_b32_e32 v92, v0
	v_mov_b32_e32 v93, v0
	v_mov_b32_e32 v94, v0
	v_mov_b32_e32 v95, v0
	v_mov_b32_e32 v104, v0
	v_mov_b32_e32 v105, v0
	v_mov_b32_e32 v106, v0
	v_mov_b32_e32 v107, v0
	v_mov_b32_e32 v108, v0
	v_mov_b32_e32 v109, v0
	v_mov_b32_e32 v110, v0
	v_mov_b32_e32 v111, v0
	v_mov_b32_e32 v120, v0
	v_mov_b32_e32 v121, v0
	v_mov_b32_e32 v122, v0
	v_mov_b32_e32 v123, v0
	v_mov_b32_e32 v124, v0
	v_mov_b32_e32 v125, v0
	v_mov_b32_e32 v126, v0
	v_mov_b32_e32 v127, v0
